# sb attention dynamic queue hands out single items (finer tail balance)
# speedup vs baseline: 1.0122x; 1.0053x over previous
; __device__ __forceinline__ void run_phase(const Args& a, const int ph, LAS unsigned char* lds, const int tid, const int rpt) {
;     ...
;                       for (;;) { int it0 = 0; if (lane == 0) it0 = (int)atomicAdd(qctr, 2u); it0 = nstat + __builtin_amdgcn_readfirstlane(it0); if (it0 >= 12 * 1024) break;
;                           for (int it = it0; it < it0 + 2; ++it) sb_item(hbuf, kmax2, mixed, vT, it, lane); } }
.LBB0_277:
	v_mov_b32_e32 v4, 0
	s_and_saveexec_b64 s[0:1], s[36:37]
	s_cbranch_execz .LBB0_281
	s_mov_b64 s[22:23], exec
	v_mbcnt_lo_u32_b32 v4, s22, 0
	v_mbcnt_hi_u32_b32 v4, s23, v4
	v_cmp_eq_u32_e32 vcc, 0, v4
	s_and_saveexec_b64 s[20:21], vcc
	s_cbranch_execz .LBB0_280
	s_bcnt1_i32_b64 s12, s[22:23]
	v_readlane_b32 s22, v249, 7
	v_mov_b32_e32 v5, s12
	v_readlane_b32 s23, v249, 8
	v_readlane_b32 s98, v251, 8
	s_sub_u32 s98, s22, s98
	s_mul_i32 s98, s98, 3
	v_readlane_b32 s99, v251, 37
	s_lshl_b32 s99, s99, 5
	s_add_i32 s98, s98, s99
	s_add_u32 s22, s22, s98
	s_addc_u32 s23, s23, 0
	s_nop 4
	global_atomic_add v5, v33, v5, s[22:23] sc0
.LBB0_280:
	s_or_b64 exec, exec, s[20:21]
	s_waitcnt vmcnt(0)
	v_readfirstlane_b32 s12, v5
	s_nop 1
	v_add_u32_e32 v4, s12, v4

; __device__ __forceinline__ unsigned pk2(float lo, float hi) { unsigned r; asm("v_cvt_pk_bf16_f32 %0, %1, %2" : "=v"(r) : "v"(lo), "v"(hi)); return r; }
; __device__ __forceinline__ void sb_item(const bf16_t* hbuf, const float* kmax2, bf16_t* mixed, LAS bf16_t* vT, int item, int lane) {
;     ...
;     for (int et = 0; et < 4; ++et) { u32x2 w; w.x = pk2(O[et][0], O[et][1]); w.y = pk2(O[et][2], O[et][3]);
;         *(u32x2*)(mixed + (row0 + r) * 1024 + M_SB + h * 64 + 16 * et + 4 * q) = w; }
; __device__ __forceinline__ void run_phase(const Args& a, const int ph, LAS unsigned char* lds, const int tid, const int rpt) {
;     ...
;                           for (int it = it0; it < it0 + 2; ++it) sb_item(hbuf, kmax2, mixed, vT, it, lane); } }
.LBB0_282:
	v_lshlrev_b64 v[4:5], 11, v[124:125]
	v_lshl_add_u64 v[4:5], s[68:69], 0, v[4:5]
	v_lshl_add_u64 v[4:5], s[20:21], 1, v[4:5]
	v_lshl_add_u64 v[4:5], v[120:121], 1, v[4:5]
	v_cvt_pk_bf16_f32 v6, v48, v49
	v_cvt_pk_bf16_f32 v7, v50, v51
	s_and_b64 vcc, exec, s[0:1]
	global_store_dwordx2 v[4:5], v[6:7], off offset:512
	v_cvt_pk_bf16_f32 v6, v76, v77
	v_cvt_pk_bf16_f32 v7, v78, v79
	s_add_i32 s0, s15, 1
	global_store_dwordx2 v[4:5], v[6:7], off offset:544
	v_cvt_pk_bf16_f32 v6, v64, v65
	v_cvt_pk_bf16_f32 v7, v66, v67
	s_cmp_ge_i32 s15, s12
	s_mov_b32 s15, s0
	global_store_dwordx2 v[4:5], v[6:7], off offset:576
	v_cvt_pk_bf16_f32 v6, v52, v53
	v_cvt_pk_bf16_f32 v7, v54, v55
	global_store_dwordx2 v[4:5], v[6:7], off offset:608
	s_cbranch_scc1 .LBB0_275
